# A-attn: bucket-uniform flag + uniform bias prefetched one tile ahead (one LDS round trip less per tile); V^T staged k-group-contiguous so each V fragment is one ds_read_b128 (A, C, B/D units)
# speedup vs baseline: 1.0177x; 1.0177x over previous
; #define ATT_LOAD(kt) do { const long kb_ = (long)(kt) * 64; \
;         rk0 = *(const u32x4*)(a.k + (kb_ + kkey0) * a.k_rs + kpart0 * 8); \
;         if (DQK == 96 && tid < 256) rk1 = *(const u32x4*)(a.k + (kb_ + kkey1) * a.k_rs + kpart1 * 8); \
;         rv0 = *(const u32x2*)(a.v + (kb_ + 2 * vkp) * a.v_rs + vdg * 4); rv1 = *(const u32x2*)(a.v + (kb_ + 2 * vkp + 1) * a.v_rs + vdg * 4); } while (0)
; template <int DQK, int MODE>
; __device__ __forceinline__ void attn_unit(LAS unsigned char* lds, const AttnArgs& a, const unsigned char* lut) {
;     ...
;     bf16x8 qf[2][DQK / 32];
; #pragma unroll
;     for (int qt = 0; qt < 2; ++qt)
; #pragma unroll
;         for (int ks = 0; ks < DQK / 32; ++ks) qf[qt][ks] = *(const bf16x8*)(a.q + (long)(qi + qt * 16) * a.q_rs + ks * 32 + lg * 8);
;     float lsum[2]; lsum[0] = (lg == 0) ? a.l_init : 0.f; lsum[1] = lsum[0];
;     const float nb = -a.bound;
;     f32x4 o[2][4];
; #pragma unroll
;     for (int qt = 0; qt < 2; ++qt)
; #pragma unroll
;         for (int d = 0; d < 4; ++d) o[qt][d] = (f32x4){0.f, 0.f, 0.f, 0.f};
;     u32x4 rk0, rk1; u32x2 rv0, rv1;
;     const int kkey0 = tid / KCH, kpart0 = tid % KCH; const int kkey1 = (tid + 512) / KCH, kpart1 = (tid + 512) % KCH;
;     const int vkp = tid & 31, vdg = tid >> 5;
;     ...
;     ATT_LOAD(kt_lo);
;     ATT_STORE(0);
;     if (kt_lo < kt_hi) ATT_LOAD(kt_lo + 1);
;     unsigned long long mwn0 = 0ull, mwn1 = 0ull;
;     if (MODE == 2) { mwn0 = a.mask[(long)qi * 128 + kt_lo]; mwn1 = a.mask[(long)(qi + 16) * 128 + kt_lo]; }
;     __syncthreads();
.LBB0_327:
	s_or_b64 exec, exec, s[0:1]
	s_mul_i32 s18, s38, 0x9800000
	s_mul_hi_i32 s14, s38, 0x9800000
	s_add_u32 s20, s34, s18
	s_addc_u32 s21, s35, s14
	s_lshl_b32 s0, s17, 6
	s_ashr_i32 s1, s0, 31
	s_lshl_b64 s[40:41], s[0:1], 1
	s_add_u32 s30, s20, s40
	s_addc_u32 s31, s21, s41
	s_ashr_i32 s17, s19, 6
	s_lshl_b32 s0, s17, 5
	s_sub_i32 s13, s0, s13
	v_and_b32_e32 v9, 15, v8
	s_addk_i32 s13, 0x1f00
	v_bfe_u32 v10, v8, 4, 2
	v_or_b32_e32 v118, s13, v9
	v_lshlrev_b32_e32 v0, 4, v10
	s_movk_i32 s19, 0x2600
	v_or_b32_e32 v114, 16, v118
	v_lshl_add_u64 v[2:3], s[30:31], 0, v[0:1]
	v_mad_i64_i32 v[120:121], s[0:1], v118, s19, 0
	v_mad_i64_i32 v[116:117], s[0:1], v114, s19, 0
	v_lshl_add_u64 v[4:5], v[120:121], 1, v[2:3]
	v_lshl_add_u64 v[2:3], v[116:117], 1, v[2:3]
	global_load_dwordx4 v[26:29], v[4:5], off
	global_load_dwordx4 v[30:33], v[4:5], off offset:64
	global_load_dwordx4 v[34:37], v[2:3], off
	global_load_dwordx4 v[38:41], v[2:3], off offset:64
	v_ashrrev_i32_e32 v2, 31, v8
	v_lshrrev_b32_e32 v2, 29, v2
	v_add_u32_e32 v2, v8, v2
	v_ashrrev_i32_e32 v11, 3, v2
	v_and_b32_e32 v2, -8, v2
	v_lshlrev_b32_e32 v6, 1, v8
	s_waitcnt vmcnt(0)
	v_sub_u32_e32 v16, v8, v2
	v_mov_b64_e32 v[2:3], s[30:31]
	v_and_b32_e32 v17, 62, v6
	v_ashrrev_i32_e32 v18, 3, v8
	v_mad_i64_i32 v[4:5], s[0:1], v11, s4, v[2:3]
	v_mad_u64_u32 v[12:13], s[0:1], v17, s4, v[2:3]
	v_and_b32_e32 v2, -4, v18
	v_lshlrev_b32_e32 v122, 3, v16
	v_ashrrev_i32_e32 v3, 31, v2
	v_ashrrev_i32_e32 v123, 31, v122
	s_mov_b64 s[0:1], 0x800
	v_lshlrev_b64 v[14:15], 1, v[2:3]
	v_lshl_add_u64 v[4:5], v[122:123], 1, v[4:5]
	v_lshl_add_u64 v[6:7], v[12:13], 0, s[0:1]
	v_lshl_add_u64 v[12:13], v[12:13], 0, v[14:15]
	global_load_dwordx4 v[46:49], v[4:5], off offset:1024
	global_load_dwordx2 v[124:125], v[12:13], off offset:2048
	v_lshl_add_u64 v[12:13], v[6:7], 0, v[14:15]
	s_movk_i32 s0, 0x4000
	v_add_co_u32_e32 v12, vcc, s0, v12
	s_movk_i32 s0, 0x48
	s_nop 0
	v_addc_co_u32_e32 v13, vcc, 0, v13, vcc
	global_load_dwordx2 v[126:127], v[12:13], off offset:3072
	v_mul_lo_u32 v12, v11, s0
	v_lshlrev_b32_e32 v61, 1, v12
	v_lshlrev_b32_e32 v12, 4, v16
	v_mul_lo_u32 v13, v2, s0
	v_add3_u32 v12, 0, v61, v12
	v_lshlrev_b32_e32 v156, 1, v13
	v_and_b32_e32 v19, 32, v17
	v_lshlrev_b32_e32 v157, 1, v19
	v_and_b32_e32 v19, 12, v17
	v_lshl_or_b32 v157, v19, 2, v157
	v_and_b32_e32 v19, 16, v17
	v_lshrrev_b32_e32 v19, 1, v19
	v_or_b32_e32 v157, v157, v19
	v_and_b32_e32 v19, 2, v17
	v_lshl_or_b32 v157, v19, 1, v157
	v_add3_u32 v13, 0, v156, v157
	v_add_u32_e32 v15, 0x3800, v13
	s_cmp_gt_i32 s12, 0
	s_waitcnt vmcnt(2)
	ds_write_b128 v12, v[46:49]
	s_waitcnt vmcnt(1)
	v_and_b32_e32 v12, 0xffff, v124
	v_lshrrev_b32_e32 v14, 16, v124
	s_waitcnt vmcnt(0)
	v_lshl_or_b32 v12, v126, 16, v12
	v_and_or_b32 v14, v126, s69, v14
	ds_write2_b32 v15, v12, v14 offset1:36
	v_and_b32_e32 v12, 0xffff, v125
	v_lshl_or_b32 v12, v127, 16, v12
	ds_write_b32 v13, v12 offset:14624
	v_or_b32_e32 v13, 3, v18
	v_mul_lo_u32 v13, v13, s0
	v_lshrrev_b32_e32 v12, 16, v125
	v_lshlrev_b32_e32 v158, 1, v13
	v_and_or_b32 v12, v127, s69, v12
	v_add3_u32 v13, 0, v158, v157
	ds_write_b32 v13, v12 offset:14336
	s_cbranch_scc0 .LBB0_329
	v_add_co_u32_e32 v4, vcc, 0x130000, v4
	v_lshl_add_u64 v[6:7], v[2:3], 1, v[6:7]
	s_nop 0
	v_addc_co_u32_e32 v5, vcc, 0, v5, vcc
	v_add_co_u32_e32 v12, vcc, 0x130000, v6
	s_nop 1
	v_addc_co_u32_e32 v13, vcc, 0, v7, vcc
	global_load_dwordx4 v[46:49], v[4:5], off offset:1024
	global_load_dwordx2 v[124:125], v[12:13], off
	v_add_co_u32_e32 v4, vcc, 0x134000, v6
	s_nop 1
	v_addc_co_u32_e32 v5, vcc, 0, v7, vcc
	global_load_dwordx2 v[126:127], v[4:5], off offset:3072
.LBB0_329:
	s_ashr_i32 s39, s38, 31
	s_lshl_b64 s[0:1], s[38:39], 23
	v_ashrrev_i32_e32 v119, 31, v118
	s_add_u32 s20, s72, s0
	v_ashrrev_i32_e32 v115, 31, v114
	s_addc_u32 s21, s73, s1
	v_lshlrev_b64 v[4:5], 10, v[118:119]
	v_lshl_add_u64 v[12:13], s[20:21], 0, v[4:5]
	v_lshlrev_b64 v[6:7], 10, v[114:115]
	v_lshl_add_u64 v[14:15], s[20:21], 0, v[6:7]
	global_load_dwordx2 v[62:63], v[12:13], off
	global_load_dwordx2 v[64:65], v[14:15], off
	s_cmp_lt_i32 s12, 0
	v_lshlrev_b32_e32 v54, 2, v10
	s_waitcnt lgkmcnt(0)
	s_barrier
	s_cbranch_scc1 .LBB0_309
	s_or_b32 s13, s13, 31
	v_readlane_b32 s19, v254, 0
	s_add_u32 s0, s19, s0
	v_readlane_b32 s19, v254, 1
	s_addc_u32 s1, s19, s1
	v_lshl_add_u64 v[128:129], s[0:1], 0, v[6:7]
	v_lshl_add_u64 v[130:131], s[0:1], 0, v[4:5]
	s_add_u32 s0, s18, s40
	s_addc_u32 s1, s14, s41
	v_and_b32_e32 v6, 31, v8
	v_mov_b64_e32 v[4:5], s[0:1]
	s_mov_b32 s14, 0x9800
	s_add_u32 s0, s0, 0xcb2a500
	v_lshlrev_b32_e32 v159, 3, v10
	v_mad_i64_i32 v[10:11], s[20:21], v11, s4, 0
	v_mad_u64_u32 v[4:5], s[18:19], v6, s14, v[4:5]
	s_addc_u32 s1, s1, 0
	v_lshl_add_u64 v[132:133], v[2:3], 1, v[4:5]
	v_lshl_add_u64 v[2:3], s[0:1], 0, v[10:11]
	s_lshl_b32 s0, s15, 10
	s_lshl_b32 s1, s17, 7
	s_add_i32 s0, s0, s1
	v_lshl_add_u64 v[134:135], v[122:123], 1, v[2:3]
	v_lshl_or_b32 v2, v9, 2, s0
	s_lshl_b32 s16, s16, 10
	v_sub_u32_e32 v2, v2, v0
	v_mov_b32_e32 v4, v1
	v_mov_b32_e32 v5, v1
	s_mul_i32 s20, s17, 0x84
	v_mul_u32_u24_e32 v160, 0x90, v9
	v_xor_b32_e32 v56, 0x80000000, v55
	s_sub_i32 s1, s0, s16
	v_subrev_u32_e32 v123, s16, v2
	v_mov_b32_e32 v2, v1
	v_mov_b32_e32 v3, v1
	v_mov_b32_e32 v94, 0
	v_mov_b64_e32 v[8:9], v[4:5]
	v_mov_b64_e32 v[12:13], v[4:5]
	v_mov_b64_e32 v[16:17], v[4:5]
	v_mov_b64_e32 v[20:21], v[4:5]
	v_mov_b64_e32 v[24:25], v[4:5]
	v_mov_b64_e32 v[44:45], v[4:5]
	v_mov_b64_e32 v[52:53], v[4:5]
	v_mov_b32_e32 v57, v56
	v_mov_b32_e32 v58, v56
	v_mov_b32_e32 v59, v56
	v_mov_b32_e32 v60, v54
	s_add_i32 s14, s20, 0x14800
	s_add_i32 s15, s1, 0x13d80
	s_lshl_b32 s0, s17, 8
	s_add_i32 s0, s0, 0x16000
	v_mbcnt_lo_u32_b32 v161, -1, 0
	v_mbcnt_hi_u32_b32 v161, -1, v161
	v_mov_b32_e32 v162, s0
	v_lshl_add_u32 v163, v161, 2, v162
	v_mov_b32_e32 v164, 0xf149f2ca
	v_mov_b32_e32 v165, s14
	v_mov_b32_e32 v161, s15
	ds_read_u8 v97, v165
	ds_read_b32 v217, v161
	s_waitcnt lgkmcnt(0)
	s_mov_b32 s16, 0
	v_mov_b32_e32 v136, v1
	v_mov_b32_e32 v137, v1
	v_mov_b64_e32 v[6:7], v[2:3]
	v_mov_b64_e32 v[10:11], v[2:3]
	v_mov_b64_e32 v[14:15], v[2:3]
	v_mov_b64_e32 v[18:19], v[2:3]
	v_mov_b64_e32 v[22:23], v[2:3]
	v_mov_b64_e32 v[42:43], v[2:3]
	v_mov_b64_e32 v[50:51], v[2:3]
	s_mov_b32 s17, 0
	v_mov_b32_e32 v95, v94

; template <int DQK, int VAR> ...
;     ...
;     for (int ch = 0; ch < 2; ++ch) {
;         bf16x8 kfr[2][DQK / 32];
; #pragma unroll
;         for (int c = 0; c < 2; ++c)
; #pragma unroll
;             for (int ks = 0; ks < DQK / 32; ++ks) kfr[c][ks] = *(const LAS bf16x8*)(sK + ((ch * 2 + c) * 16 + lr) * KP + ks * 32 + lg * 8);
;         __builtin_amdgcn_sched_barrier(0);
;         __builtin_amdgcn_s_setprio(1);
; #pragma unroll
;         for (int c = 0; c < 2; ++c) {
; template <int DQK, int MODE>
; __device__ __forceinline__ void attn_unit(LAS unsigned char* lds, const AttnArgs& a, const unsigned char* lut) {
;     ...
;     for (int kt = kt_lo; kt <= kt_hi; ++kt) {
;         const int cur = (kt - kt_lo) & 1;
;         if (kt < kt_hi) ATT_STORE(cur ^ 1);
;         if (kt + 1 < kt_hi) ATT_LOAD(kt + 2);
;         const unsigned long long mwc0 = mwn0, mwc1 = mwn1;
;         if (MODE == 2 && kt < kt_hi) { mwn0 = a.mask[(long)qi * 128 + kt + 1]; mwn1 = a.mask[(long)(qi + 16) * 128 + kt + 1]; }
;         const LAS bf16_t* sK = (const LAS bf16_t*)(lds + cur * 24576); const LAS bf16_t* sVt = (const LAS bf16_t*)(lds + cur * 24576 + 14336);
;         const int key0 = kt * 64;
;         bool skip = key0 > wq_max;
;         if (MODE == 1) skip = skip || (key0 + 63 < wq_min - a.maxdist);
;         if (!skip) {
;             unsigned mlo[2] = {0u, 0u}, mhi[2] = {0u, 0u};
;             if (MODE == 0) {
;                 if (key0 + 63 <= wq_min) attn_tile<DQK, 0>(sK, sVt, sBias, qf, o, lsum, qi, key0, 0, mlo, mhi, nb, lr, lg);
;                 else attn_tile<DQK, 1>(sK, sVt, sBias, qf, o, lsum, qi, key0, 0, mlo, mhi, nb, lr, lg);
;             } else if (MODE == 1) {
;                 attn_tile<DQK, 2>(sK, sVt, sBias, qf, o, lsum, qi, key0, a.maxdist, mlo, mhi, nb, lr, lg);
;             } else {
;                 const unsigned long long w0 = mwc0 >> (lg * 4), w1 = mwc1 >> (lg * 4);
;                 mlo[0] = (unsigned)w0; mhi[0] = (unsigned)(w0 >> 32); mlo[1] = (unsigned)w1; mhi[1] = (unsigned)(w1 >> 32);
;                 const int uni = __builtin_amdgcn_readfirstlane((int)sUni[wid * 132 + kt]);
;                 if (uni) { const float ub = sBias[96 + wq_min - key0]; attn_tile<DQK, 3>(sK, sVt, sBias, qf, o, lsum, qi, key0, 0, mlo, mhi, nb + ub, lr, lg); }
;                 else attn_tile<DQK, 4>(sK, sVt, sBias, qf, o, lsum, qi, key0, 0, mlo, mhi, nb, lr, lg);
.LBB0_338:
	s_mulk_i32 s19, 0x6000
	v_lshrrev_b64 v[62:63], v60, v[62:63]
	v_lshrrev_b64 v[64:65], v54, v[64:65]
	s_add_i32 s0, s19, 0
	v_add3_u32 v96, s0, v0, v160
	s_movk_i32 s0, 0xf0
	v_lshlrev_b32_e32 v69, 4, v62
	v_lshrrev_b32_e32 v70, 12, v62
	v_lshlrev_b32_e32 v71, 4, v63
	v_lshrrev_b32_e32 v72, 12, v63
	v_lshlrev_b32_e32 v73, 4, v64
	v_lshrrev_b32_e32 v74, 12, v64
	v_lshlrev_b32_e32 v75, 4, v65
	v_lshrrev_b32_e32 v76, 12, v65
	v_and_or_b32 v69, v69, s0, v162
	v_and_or_b32 v70, v70, s0, v162
	v_and_or_b32 v71, v71, s0, v162
	v_and_or_b32 v72, v72, s0, v162
	v_and_or_b32 v73, v73, s0, v162
	v_and_or_b32 v74, v74, s0, v162
	v_and_or_b32 v75, v75, s0, v162
	v_and_or_b32 v76, v76, s0, v162
	s_mov_b32 vcc_lo, 0x76543210
	s_mov_b32 vcc_hi, 0xfedcba98
	v_readfirstlane_b32 s1, v97
	v_sub_f32_e32 v78, v217, v55
	s_nop 0
	s_cmp_lg_u32 s1, 0
	s_cselect_b64 s[36:37], -1, 0
	v_cndmask_b32_e64 v77, v56, v78, s[36:37]
	v_cndmask_b32_e32 v77, v164, v77, vcc
	ds_write_b32 v163, v77
	ds_read_b128 v[80:83], v69
	ds_read_b128 v[84:87], v73
	ds_read_b128 v[148:151], v96
	ds_read_b128 v[152:155], v96 offset:64
	ds_read_b128 v[88:91], v70
	ds_read_b128 v[200:203], v74
	ds_read_b128 v[166:169], v96 offset:2304
	ds_read_b128 v[170:173], v96 offset:2368
	ds_read_b128 v[98:101], v71
	ds_read_b128 v[102:105], v75
	ds_read_b128 v[106:109], v72
	ds_read_b128 v[110:113], v76
	s_setprio 1
	s_waitcnt lgkmcnt(9)
	v_mfma_f32_16x16x32_bf16 v[80:83], v[148:151], v[26:29], v[80:83]
	v_mfma_f32_16x16x32_bf16 v[84:87], v[148:151], v[34:37], v[84:87]
	ds_read_b128 v[174:177], v96 offset:4608
	ds_read_b128 v[178:181], v96 offset:4672
	ds_read_b128 v[182:185], v96 offset:6912
	ds_read_b128 v[186:189], v96 offset:6976
	s_waitcnt lgkmcnt(12)
	v_mfma_f32_16x16x32_bf16 v[80:83], v[152:155], v[30:33], v[80:83]
	v_mfma_f32_16x16x32_bf16 v[84:87], v[152:155], v[38:41], v[84:87]
	s_waitcnt lgkmcnt(9)
	v_mfma_f32_16x16x32_bf16 v[88:91], v[166:169], v[26:29], v[88:91]
	v_mfma_f32_16x16x32_bf16 v[200:203], v[166:169], v[34:37], v[200:203]
	s_waitcnt lgkmcnt(8)
	v_mfma_f32_16x16x32_bf16 v[88:91], v[170:173], v[30:33], v[88:91]
	v_mfma_f32_16x16x32_bf16 v[200:203], v[170:173], v[38:41], v[200:203]
	s_waitcnt lgkmcnt(3)
	v_mfma_f32_16x16x32_bf16 v[98:101], v[174:177], v[26:29], v[98:101]
	v_mfma_f32_16x16x32_bf16 v[102:105], v[174:177], v[34:37], v[102:105]
	s_waitcnt lgkmcnt(2)
	v_mfma_f32_16x16x32_bf16 v[98:101], v[178:181], v[30:33], v[98:101]
	v_mfma_f32_16x16x32_bf16 v[102:105], v[178:181], v[38:41], v[102:105]
	s_waitcnt lgkmcnt(1)
	v_mfma_f32_16x16x32_bf16 v[106:109], v[182:185], v[26:29], v[106:109]
	v_mfma_f32_16x16x32_bf16 v[110:113], v[182:185], v[34:37], v[110:113]
	s_waitcnt lgkmcnt(0)
	v_mfma_f32_16x16x32_bf16 v[106:109], v[186:189], v[30:33], v[106:109]
	v_mfma_f32_16x16x32_bf16 v[110:113], v[186:189], v[38:41], v[110:113]
	s_setprio 0
	s_add_i32 s0, s14, 1
	v_mov_b32_e32 v161, s0
	s_add_i32 s0, s15, 0xffffff00
	v_mov_b32_e32 v165, s0
	ds_read_u8 v97, v161
	ds_read_b32 v217, v165
	s_cmp_eq_u32 s1, 0
	s_cbranch_scc1 .Lmy_a_nonuni
	ds_read_b128 v[148:151], v96 offset:14336
	ds_read_b128 v[152:155], v96 offset:16640
	ds_read_b128 v[166:169], v96 offset:18944
	ds_read_b128 v[170:173], v96 offset:21248
	ds_read_b128 v[174:177], v96 offset:14400
	ds_read_b128 v[178:181], v96 offset:16704
	ds_read_b128 v[182:185], v96 offset:19008
	ds_read_b128 v[186:189], v96 offset:21312

; #define LAS __attribute__((address_space(3)))
; __device__ __forceinline__ float fexp2(float x) { return __builtin_amdgcn_exp2f(x); }
; template <int DQK, int VAR> ...
;     ...
; #pragma unroll
;     for (int kk = 0; kk < 2; ++kk)
; #pragma unroll
;         for (int dt = 0; dt < 4; ++dt) {
;             const LAS bf16_t* vp = sVt + (dt * 16 + lr) * VP + kk * 32 + lg * 4;
;             const u32x2 v0 = *(const LAS u32x2*)vp, v1 = *(const LAS u32x2*)(vp + 16);
;             vfr[kk][dt].x = v0.x; vfr[kk][dt].y = v0.y; vfr[kk][dt].z = v1.x; vfr[kk][dt].w = v1.y;
;         }
;     __builtin_amdgcn_sched_barrier(0);
; #pragma unroll
;     for (int qt = 0; qt < 2; ++qt) {
;         const int dq = qi + qt * 16 - key0 - lg * 4;
;         const LAS float* bp = sBias + (dq + 33);
;         float ps = 0.f;
; #pragma unroll
;         for (int c = 0; c < 4; ++c)
; #pragma unroll
;             for (int j = 0; j < 4; ++j) {
;                 float val = s[qt][c][j]; float pv;
;                 if (VAR == 0) pv = fexp2(val);
;                 else if (VAR == 1) { pv = fexp2(val); pv = (dq >= c * 16 + j) ? pv : 0.f; }
;                 else if (VAR == 2) { pv = fexp2(val + bp[63 - (c * 16 + j)]); }
;                 else if (VAR == 3) { pv = fexp2(val); pv = __uint_as_float(__float_as_uint(pv) & (unsigned)__builtin_amdgcn_sbfe((int)(c < 2 ? mlo[qt] : mhi[qt]), (c & 1) * 16 + j, 1)); }
;                 else { pv = fexp2(val + bp[63 - (c * 16 + j)]); pv = __uint_as_float(__float_as_uint(pv) & (unsigned)__builtin_amdgcn_sbfe((int)(c < 2 ? mlo[qt] : mhi[qt]), (c & 1) * 16 + j, 1)); }
.Lmy_a_nonuni:
	v_add_u32_e32 v165, 0x13cb4, v123
	ds_read2_b32 v[78:79], v165 offset0:66 offset1:67
	ds_read2_b32 v[190:191], v165 offset0:64 offset1:65
	ds_read2_b32 v[136:137], v165 offset0:50 offset1:51
	ds_read2_b32 v[214:215], v165 offset0:48 offset1:49
	ds_read2_b32 v[238:239], v165 offset0:34 offset1:35
	ds_read2_b32 v[92:93], v165 offset0:32 offset1:33
	ds_read2_b32 v[218:219], v165 offset0:18 offset1:19
	ds_read2_b32 v[220:221], v165 offset0:16 offset1:17
	ds_read2_b32 v[222:223], v165 offset0:2 offset1:3
	ds_read2_b32 v[224:225], v165 offset1:1
	ds_read_b128 v[148:151], v96 offset:14336
	ds_read_b128 v[152:155], v96 offset:16640
	s_waitcnt lgkmcnt(10)
	v_add_f32_e32 v84, v84, v79
	v_add_f32_e32 v85, v85, v78
	v_add_f32_e32 v86, v86, v191
	v_add_f32_e32 v87, v87, v190
	ds_read_b128 v[166:169], v96 offset:18944
	ds_read_b128 v[170:173], v96 offset:21248
	s_waitcnt lgkmcnt(10)
	v_add_f32_e32 v80, v80, v137
	v_add_f32_e32 v81, v81, v136
	v_add_f32_e32 v82, v82, v215
	v_add_f32_e32 v83, v83, v214
	v_add_f32_e32 v200, v200, v137
	v_add_f32_e32 v201, v201, v136
	v_add_f32_e32 v202, v202, v215
	v_add_f32_e32 v203, v203, v214
	ds_read_b128 v[174:177], v96 offset:14400
	ds_read_b128 v[178:181], v96 offset:16704
	s_waitcnt lgkmcnt(10)
	v_add_f32_e32 v88, v88, v239
	v_add_f32_e32 v89, v89, v238
	v_add_f32_e32 v90, v90, v93
	v_add_f32_e32 v91, v91, v92
	v_add_f32_e32 v102, v102, v239
	v_add_f32_e32 v103, v103, v238
	v_add_f32_e32 v104, v104, v93
	v_add_f32_e32 v105, v105, v92
	ds_read_b128 v[182:185], v96 offset:19008
	ds_read_b128 v[186:189], v96 offset:21312
	s_waitcnt lgkmcnt(10)
	v_add_f32_e32 v98, v98, v219
	v_add_f32_e32 v99, v99, v218
	v_add_f32_e32 v100, v100, v221
	v_add_f32_e32 v101, v101, v220
	v_add_f32_e32 v110, v110, v219
	v_add_f32_e32 v111, v111, v218
	v_add_f32_e32 v112, v112, v221
	v_add_f32_e32 v113, v113, v220
	s_waitcnt lgkmcnt(8)
	v_add_f32_e32 v106, v106, v223
	v_add_f32_e32 v107, v107, v222
	v_add_f32_e32 v108, v108, v225
	v_add_f32_e32 v109, v109, v224
	s_branch .Lmy_a_exp

; #define ATT_LOAD(kt) do { const long kb_ = (long)(kt) * 64; \
;         rk0 = *(const u32x4*)(a.k + (kb_ + kkey0) * a.k_rs + kpart0 * 8); \
;         if (DQK == 96 && tid < 256) rk1 = *(const u32x4*)(a.k + (kb_ + kkey1) * a.k_rs + kpart1 * 8); \
;         rv0 = *(const u32x2*)(a.v + (kb_ + 2 * vkp) * a.v_rs + vdg * 4); rv1 = *(const u32x2*)(a.v + (kb_ + 2 * vkp + 1) * a.v_rs + vdg * 4); } while (0)
; template <int DQK, int MODE>
; __device__ __forceinline__ void attn_unit(LAS unsigned char* lds, const AttnArgs& a, const unsigned char* lut) {
;     ...
;     bf16x8 qf[2][DQK / 32];
; #pragma unroll
;     for (int qt = 0; qt < 2; ++qt)
; #pragma unroll
;         for (int ks = 0; ks < DQK / 32; ++ks) qf[qt][ks] = *(const bf16x8*)(a.q + (long)(qi + qt * 16) * a.q_rs + ks * 32 + lg * 8);
;     float lsum[2]; lsum[0] = (lg == 0) ? a.l_init : 0.f; lsum[1] = lsum[0];
;     const float nb = -a.bound;
;     f32x4 o[2][4];
; #pragma unroll
;     for (int qt = 0; qt < 2; ++qt)
; #pragma unroll
;         for (int d = 0; d < 4; ++d) o[qt][d] = (f32x4){0.f, 0.f, 0.f, 0.f};
;     u32x4 rk0, rk1; u32x2 rv0, rv1;
;     const int kkey0 = tid / KCH, kpart0 = tid % KCH; const int kkey1 = (tid + 512) / KCH, kpart1 = (tid + 512) % KCH;
;     const int vkp = tid & 31, vdg = tid >> 5;
;     ...
;     ATT_LOAD(kt_lo);
;     ATT_STORE(0);
;     if (kt_lo < kt_hi) ATT_LOAD(kt_lo + 1);
;     unsigned long long mwn0 = 0ull, mwn1 = 0ull;
;     if (MODE == 2) { mwn0 = a.mask[(long)qi * 128 + kt_lo]; mwn1 = a.mask[(long)(qi + 16) * 128 + kt_lo]; }
;     __syncthreads();
.LBB0_364:
	s_or_b64 exec, exec, s[54:55]
	v_mov_b32_e32 v8, v192
	v_mov_b32_e32 v113, v1
	v_readfirstlane_b32 s0, v8
	s_ashr_i32 s0, s0, 1
	s_and_b32 s18, s0, 0xffffffe0
	v_and_b32_e32 v4, 15, v8
	v_bfe_u32 v10, v8, 4, 2
	s_add_i32 s18, s18, s14
	v_or_b32_e32 v162, s18, v4
	s_sub_i32 s0, s14, s16
	v_lshlrev_b32_e32 v112, 4, v10
	s_max_i32 s17, s0, 0
	v_lshl_add_u64 v[2:3], s[36:37], 0, v[112:113]
	v_mad_i64_i32 v[6:7], s[0:1], s52, v162, 0
	v_lshl_add_u64 v[6:7], v[6:7], 1, v[2:3]
	v_or_b32_e32 v113, 16, v162
	global_load_dwordx4 v[26:29], v[6:7], off
	global_load_dwordx4 v[30:33], v[6:7], off offset:64
	v_mad_i64_i32 v[6:7], s[0:1], s52, v113, 0
	v_lshl_add_u64 v[2:3], v[6:7], 1, v[2:3]
	global_load_dwordx4 v[34:37], v[2:3], off
	global_load_dwordx4 v[38:41], v[2:3], off offset:64
	v_ashrrev_i32_e32 v2, 31, v8
	v_lshrrev_b32_e32 v2, 29, v2
	v_add_u32_e32 v3, v8, v2
	s_ashr_i32 s0, s14, 6
	v_ashrrev_i32_e32 v2, 3, v3
	v_and_b32_e32 v3, -8, v3
	s_or_b32 s14, s0, 3
	v_sub_u32_e32 v5, v8, v3
	s_and_b32 s0, s17, 0x7fffffc0
	s_mov_b32 s1, s77
	v_ashrrev_i32_e32 v3, 31, v2
	v_lshl_add_u64 v[6:7], v[2:3], 0, s[0:1]
	v_mad_u64_u32 v[12:13], s[20:21], v6, s52, 0
	v_mad_i32_i24 v13, v7, s52, v13
	v_lshlrev_b32_e32 v114, 3, v5
	v_lshl_add_u64 v[6:7], v[12:13], 1, s[38:39]
	v_ashrrev_i32_e32 v115, 31, v114
	v_lshl_add_u64 v[6:7], v[114:115], 1, v[6:7]
	global_load_dwordx4 v[42:45], v[6:7], off
	v_lshlrev_b32_e32 v6, 1, v8
	v_and_b32_e32 v11, 62, v6
	v_ashrrev_i32_e32 v9, 3, v8
	v_or_b32_e32 v6, s0, v11
	s_waitcnt vmcnt(0)
	v_and_b32_e32 v14, -4, v9
	v_mad_u64_u32 v[6:7], s[20:21], v6, s52, 0
	v_ashrrev_i32_e32 v15, 31, v14
	v_lshl_add_u64 v[12:13], v[6:7], 1, s[56:57]
	v_lshlrev_b64 v[6:7], 1, v[14:15]
	s_lshl_b32 s76, s52, 1
	v_lshl_add_u64 v[16:17], v[12:13], 0, v[6:7]
	v_lshl_add_u64 v[12:13], v[12:13], 0, s[76:77]
	global_load_dwordx2 v[116:117], v[16:17], off
	v_lshl_add_u64 v[12:13], v[12:13], 0, v[6:7]
	global_load_dwordx2 v[118:119], v[12:13], off
	s_movk_i32 s1, 0x48
	v_mul_lo_u32 v12, v2, s1
	v_lshlrev_b32_e32 v111, 1, v12
	v_lshlrev_b32_e32 v5, 4, v5
	v_mul_lo_u32 v12, v14, s1
	v_add3_u32 v5, 0, v111, v5
	v_lshlrev_b32_e32 v163, 1, v12
	v_and_b32_e32 v13, 32, v11
	v_lshlrev_b32_e32 v164, 1, v13
	v_and_b32_e32 v13, 12, v11
	v_lshl_or_b32 v164, v13, 2, v164
	v_and_b32_e32 v13, 16, v11
	v_lshrrev_b32_e32 v13, 1, v13
	v_or_b32_e32 v164, v164, v13
	v_and_b32_e32 v13, 2, v11
	v_lshl_or_b32 v164, v13, 1, v164
	v_add3_u32 v12, 0, v163, v164
	v_add_u32_e32 v14, 0x3800, v12
	v_or_b32_e32 v9, 3, v9
	v_mul_lo_u32 v9, v9, s1
	s_lshr_b32 s13, s17, 6
	v_lshlrev_b32_e32 v165, 1, v9
	v_add3_u32 v9, 0, v165, v164
	s_cmp_ge_i32 s13, s14
	s_waitcnt vmcnt(2)
	ds_write_b128 v5, v[42:45]
	s_waitcnt vmcnt(1)
	v_and_b32_e32 v5, 0xffff, v116
	v_lshrrev_b32_e32 v13, 16, v116
	s_waitcnt vmcnt(0)
	v_lshl_or_b32 v5, v118, 16, v5
	v_and_or_b32 v13, v118, s69, v13
	ds_write2_b32 v14, v5, v13 offset1:36
	v_and_b32_e32 v5, 0xffff, v117
	v_lshl_or_b32 v5, v119, 16, v5
	ds_write_b32 v12, v5 offset:14624
	v_lshrrev_b32_e32 v5, 16, v117
	v_and_or_b32 v5, v119, s69, v5
	ds_write_b32 v9, v5 offset:14336
	s_cbranch_scc1 .LBB0_366
	s_add_i32 s20, s0, 64
	s_mov_b32 s21, s77
	v_lshl_add_u64 v[12:13], v[2:3], 0, s[20:21]
	v_mad_u64_u32 v[14:15], s[22:23], v12, s52, 0
	v_mad_i32_i24 v15, v13, s52, v15
	v_lshl_add_u64 v[12:13], v[14:15], 1, s[38:39]
	v_lshl_add_u64 v[12:13], v[114:115], 1, v[12:13]
	v_or_b32_e32 v5, s20, v11
	global_load_dwordx4 v[42:45], v[12:13], off
	v_mad_u64_u32 v[12:13], s[20:21], v5, s52, 0
	v_lshl_add_u64 v[12:13], v[12:13], 1, s[56:57]
	v_lshl_add_u64 v[14:15], v[12:13], 0, v[6:7]
	v_lshl_add_u64 v[12:13], v[12:13], 0, s[76:77]
	v_lshl_add_u64 v[12:13], v[12:13], 0, v[6:7]
	global_load_dwordx2 v[116:117], v[14:15], off
	global_load_dwordx2 v[118:119], v[12:13], off

; #define LAS __attribute__((address_space(3)))
; template <int DQK, int VAR> ...
;     ...
;     for (int ch = 0; ch < 2; ++ch) {
;         bf16x8 kfr[2][DQK / 32];
; #pragma unroll
;         for (int c = 0; c < 2; ++c)
; #pragma unroll
;             for (int ks = 0; ks < DQK / 32; ++ks) kfr[c][ks] = *(const LAS bf16x8*)(sK + ((ch * 2 + c) * 16 + lr) * KP + ks * 32 + lg * 8);
;         __builtin_amdgcn_sched_barrier(0);
;         __builtin_amdgcn_s_setprio(1);
; #pragma unroll
;         for (int c = 0; c < 2; ++c) {
;             s[0][ch * 2 + c] = (f32x4){sinit, sinit, sinit, sinit}; s[1][ch * 2 + c] = s[0][ch * 2 + c];
; #pragma unroll
;             for (int ks = 0; ks < DQK / 32; ++ks) {
;                 s[0][ch * 2 + c] = __builtin_amdgcn_mfma_f32_16x16x32_bf16(kfr[c][ks], qf[0][ks], s[0][ch * 2 + c], 0, 0, 0);
;                 s[1][ch * 2 + c] = __builtin_amdgcn_mfma_f32_16x16x32_bf16(kfr[c][ks], qf[1][ks], s[1][ch * 2 + c], 0, 0, 0);
;             }
;         }
;         __builtin_amdgcn_s_setprio(0);
;         __builtin_amdgcn_sched_barrier(0);
;     }
;     __builtin_amdgcn_s_setprio(0);
;     __builtin_amdgcn_sched_barrier(0);
; #pragma unroll
;     for (int kk = 0; kk < 2; ++kk)
; #pragma unroll
;         for (int dt = 0; dt < 4; ++dt) {
;             const LAS bf16_t* vp = sVt + (dt * 16 + lr) * VP + kk * 32 + lg * 4;
;             const u32x2 v0 = *(const LAS u32x2*)vp, v1 = *(const LAS u32x2*)(vp + 16);
;             vfr[kk][dt].x = v0.x; vfr[kk][dt].y = v0.y; vfr[kk][dt].z = v1.x; vfr[kk][dt].w = v1.y;
;         }
;     __builtin_amdgcn_sched_barrier(0);
; #pragma unroll
;     for (int qt = 0; qt < 2; ++qt) {
;         const int dq = qi + qt * 16 - key0 - lg * 4;
;         const LAS float* bp = sBias + (dq + 33);
;         float ps = 0.f;
; #pragma unroll
;         for (int c = 0; c < 4; ++c)
; #pragma unroll
;             for (int j = 0; j < 4; ++j) {
;                 float val = s[qt][c][j]; float pv;
;                 if (VAR == 0) pv = fexp2(val);
;                 else if (VAR == 1) { pv = fexp2(val); pv = (dq >= c * 16 + j) ? pv : 0.f; }
;                 else if (VAR == 2) { pv = fexp2(val + bp[63 - (c * 16 + j)]); }
;                 else if (VAR == 3) { pv = fexp2(val); pv = __uint_as_float(__float_as_uint(pv) & (unsigned)__builtin_amdgcn_sbfe((int)(c < 2 ? mlo[qt] : mhi[qt]), (c & 1) * 16 + j, 1)); }
.LBB0_373:
	s_cmp_gt_i32 s18, s15
	s_cselect_b64 s[22:23], -1, 0
	s_add_i32 s21, s18, 63
	s_cmp_lt_i32 s21, s16
	s_cselect_b64 s[38:39], -1, 0
	s_or_b64 s[22:23], s[22:23], s[38:39]
	s_and_b64 vcc, exec, s[22:23]
	s_cbranch_vccnz .LBB0_368
	s_mulk_i32 s20, 0x6000
	s_add_i32 s20, s20, 0
	v_add3_u32 v78, s20, v112, v168
	ds_read_b128 v[58:61], v78
	ds_read_b128 v[62:65], v78 offset:64
	ds_read_b128 v[66:69], v78 offset:2304
	ds_read_b128 v[70:73], v78 offset:2368
	s_setprio 1
	s_waitcnt lgkmcnt(3)
	v_mfma_f32_16x16x32_bf16 v[74:77], v[58:61], v[26:29], v[54:57]
	v_mfma_f32_16x16x32_bf16 v[58:61], v[58:61], v[34:37], v[54:57]
	s_waitcnt lgkmcnt(2)
	v_mfma_f32_16x16x32_bf16 v[132:135], v[62:65], v[30:33], v[74:77]
	v_mfma_f32_16x16x32_bf16 v[102:105], v[62:65], v[38:41], v[58:61]
	s_waitcnt lgkmcnt(1)
	v_mfma_f32_16x16x32_bf16 v[58:61], v[66:69], v[26:29], v[54:57]
	v_mfma_f32_16x16x32_bf16 v[62:65], v[66:69], v[34:37], v[54:57]
	s_waitcnt lgkmcnt(0)
	v_mfma_f32_16x16x32_bf16 v[148:151], v[70:73], v[30:33], v[58:61]
	v_mfma_f32_16x16x32_bf16 v[90:93], v[70:73], v[38:41], v[62:65]
	s_setprio 0
	s_nop 2
	ds_read_b128 v[58:61], v78 offset:4608
	ds_read_b128 v[62:65], v78 offset:4672
	ds_read_b128 v[66:69], v78 offset:6912
	ds_read_b128 v[70:73], v78 offset:6976
	s_setprio 1
	s_waitcnt lgkmcnt(3)
	v_mfma_f32_16x16x32_bf16 v[74:77], v[58:61], v[26:29], v[54:57]
	v_mfma_f32_16x16x32_bf16 v[58:61], v[58:61], v[34:37], v[54:57]
	s_waitcnt lgkmcnt(2)
	v_mfma_f32_16x16x32_bf16 v[154:157], v[62:65], v[30:33], v[74:77]
	v_mfma_f32_16x16x32_bf16 v[98:101], v[62:65], v[38:41], v[58:61]
	s_waitcnt lgkmcnt(1)
	v_mfma_f32_16x16x32_bf16 v[58:61], v[66:69], v[26:29], v[54:57]
	v_mfma_f32_16x16x32_bf16 v[62:65], v[66:69], v[34:37], v[54:57]
	s_waitcnt lgkmcnt(0)
	v_mfma_f32_16x16x32_bf16 v[106:109], v[70:73], v[30:33], v[58:61]
	v_mfma_f32_16x16x32_bf16 v[94:97], v[70:73], v[38:41], v[62:65]
	s_setprio 0
	s_setprio 0
	s_nop 2
	v_mov_b32_e32 v86, v78
	ds_read_b128 v[58:61], v86 offset:14336
	ds_read_b128 v[66:69], v86 offset:16640
	ds_read_b128 v[74:77], v86 offset:18944
	ds_read_b128 v[82:85], v86 offset:21248
	ds_read_b128 v[62:65], v86 offset:14400
	ds_read_b128 v[70:73], v86 offset:16704
	ds_read_b128 v[78:81], v86 offset:19008
	ds_read_b128 v[86:89], v86 offset:21312
	ds_read2_b32 v[178:179], v115 offset0:66 offset1:67
	ds_read2_b32 v[144:145], v115 offset0:50 offset1:51
	ds_read2_b32 v[142:143], v115 offset0:48 offset1:49
	ds_read2_b32 v[146:147], v115 offset0:34 offset1:35
	ds_read2_b32 v[160:161], v115 offset0:32 offset1:33
	s_waitcnt lgkmcnt(4)
	v_add_f32_e32 v102, v102, v179
	s_waitcnt lgkmcnt(3)
	v_add_f32_e32 v121, v132, v145
	v_exp_f32_e32 v131, v102
	v_add_f32_e32 v102, v103, v178
	v_exp_f32_e32 v130, v121
	v_add_f32_e32 v121, v133, v144
	v_exp_f32_e32 v133, v102
	ds_read2_b32 v[102:103], v115 offset0:64 offset1:65
	v_exp_f32_e32 v132, v121
	s_waitcnt lgkmcnt(3)
	v_add_f32_e32 v121, v134, v143
	v_add_f32_e32 v90, v90, v145
	v_exp_f32_e32 v134, v121
	s_waitcnt lgkmcnt(0)
	v_add_f32_e32 v103, v104, v103
	v_add_f32_e32 v121, v135, v142
	ds_read2_b32 v[170:171], v115 offset0:18 offset1:19
	ds_read2_b32 v[172:173], v115 offset0:16 offset1:17
	ds_read2_b32 v[174:175], v115 offset0:2 offset1:3
	ds_read2_b32 v[176:177], v115 offset1:1
	v_exp_f32_e32 v135, v103
	v_add_f32_e32 v102, v105, v102
	v_exp_f32_e32 v139, v90
	v_add_f32_e32 v90, v91, v144
	v_exp_f32_e32 v136, v121
	v_add_f32_e32 v121, v148, v147
	v_exp_f32_e32 v137, v102
	v_exp_f32_e32 v141, v90
	v_add_f32_e32 v90, v92, v143
	v_exp_f32_e32 v138, v121
	v_add_f32_e32 v121, v149, v146
	v_exp_f32_e32 v149, v90
	v_pk_add_f32 v[90:91], v[130:131], 0 op_sel_hi:[1,0]
	v_exp_f32_e32 v140, v121
	v_add_f32_e32 v121, v150, v161
	v_pk_add_f32 v[90:91], v[90:91], v[132:133]
	v_exp_f32_e32 v148, v121
	v_add_f32_e32 v121, v151, v160
	v_pk_add_f32 v[90:91], v[90:91], v[134:135]
	v_add_f32_e32 v92, v93, v142
	v_exp_f32_e32 v150, v121
	s_waitcnt lgkmcnt(3)
; #define LAS __attribute__((address_space(3)))
; __device__ __forceinline__ unsigned pk2(float lo, float hi) { unsigned r; asm volatile("v_cvt_pk_bf16_f32 %0, %1, %2" : "=v"(r) : "v"(lo), "v"(hi)); return r; }
; __device__ __forceinline__ float fexp2(float x) { return __builtin_amdgcn_exp2f(x); }
; template <int DQK, int VAR> ...
;     ...
;     for (int qt = 0; qt < 2; ++qt) {
;         const int dq = qi + qt * 16 - key0 - lg * 4;
;         const LAS float* bp = sBias + (dq + 33);
;         float ps = 0.f;
; #pragma unroll
;         for (int c = 0; c < 4; ++c)
; #pragma unroll
;             for (int j = 0; j < 4; ++j) {
;                 float val = s[qt][c][j]; float pv;
;                 if (VAR == 0) pv = fexp2(val);
;                 else if (VAR == 1) { pv = fexp2(val); pv = (dq >= c * 16 + j) ? pv : 0.f; }
;                 else if (VAR == 2) { pv = fexp2(val + bp[63 - (c * 16 + j)]); }
;                 else if (VAR == 3) { pv = fexp2(val); pv = __uint_as_float(__float_as_uint(pv) & (unsigned)__builtin_amdgcn_sbfe((int)(c < 2 ? mlo[qt] : mhi[qt]), (c & 1) * 16 + j, 1)); }
;                 else { pv = fexp2(val + bp[63 - (c * 16 + j)]); pv = __uint_as_float(__float_as_uint(pv) & (unsigned)__builtin_amdgcn_sbfe((int)(c < 2 ? mlo[qt] : mhi[qt]), (c & 1) * 16 + j, 1)); }
;                 s[qt][c][j] = pv; ps += pv;
;             }
;         lsum[qt] += ps;
;     }
;     __builtin_amdgcn_s_setprio(1);
; #pragma unroll
;     for (int kk = 0; kk < 2; ++kk) {
;         bf16x8 pb[2];
; #pragma unroll
;         for (int qt = 0; qt < 2; ++qt) {
;             u32x4 pw; pw.x = pk2(s[qt][2 * kk][0], s[qt][2 * kk][1]); pw.y = pk2(s[qt][2 * kk][2], s[qt][2 * kk][3]); pw.z = pk2(s[qt][2 * kk + 1][0], s[qt][2 * kk + 1][1]); pw.w = pk2(s[qt][2 * kk + 1][2], s[qt][2 * kk + 1][3]);
;             pb[qt] = __builtin_bit_cast(bf16x8, pw);
;         }
; #pragma unroll
;         for (int dt = 0; dt < 4; ++dt) {
;             const bf16x8 vf = __builtin_bit_cast(bf16x8, vfr[kk][dt]);
;             o[0][dt] = __builtin_amdgcn_mfma_f32_16x16x32_bf16(vf, pb[0], o[0][dt], 0, 0, 0);
;             o[1][dt] = __builtin_amdgcn_mfma_f32_16x16x32_bf16(vf, pb[1], o[1][dt], 0, 0, 0);
;         }
;     }
	v_add_f32_e32 v121, v154, v171
	v_pk_add_f32 v[90:91], v[90:91], v[136:137]
	v_exp_f32_e32 v151, v92
	v_add_f32_e32 v92, v98, v147
	v_exp_f32_e32 v152, v121
	v_add_f32_e32 v121, v155, v170
	v_pk_add_f32 v[90:91], v[90:91], v[138:139]
	v_exp_f32_e32 v153, v92
	v_add_f32_e32 v92, v99, v146
	v_exp_f32_e32 v154, v121
	s_waitcnt lgkmcnt(2)
	v_add_f32_e32 v121, v156, v173
	s_waitcnt lgkmcnt(1)
	v_add_f32_e32 v107, v107, v174
	v_pk_add_f32 v[90:91], v[90:91], v[140:141]
	v_exp_f32_e32 v155, v92
	v_add_f32_e32 v92, v100, v161
	v_exp_f32_e32 v156, v121
	v_add_f32_e32 v121, v157, v172
	v_exp_f32_e32 v174, v107
	s_waitcnt lgkmcnt(0)
	v_add_f32_e32 v107, v108, v177
	v_pk_add_f32 v[90:91], v[90:91], v[148:149]
	v_exp_f32_e32 v157, v92
	v_add_f32_e32 v92, v101, v160
	v_exp_f32_e32 v158, v121
	v_add_f32_e32 v106, v106, v175
	v_exp_f32_e32 v108, v107
	v_add_f32_e32 v107, v109, v176
	v_exp_f32_e32 v159, v92
	v_add_f32_e32 v92, v94, v171
	v_pk_add_f32 v[90:91], v[150:151], v[90:91]
	v_exp_f32_e32 v106, v106
	v_exp_f32_e32 v176, v107
	v_exp_f32_e32 v107, v92
	v_add_f32_e32 v92, v95, v170
	v_pk_add_f32 v[90:91], v[152:153], v[90:91]
	v_exp_f32_e32 v175, v92
	v_add_f32_e32 v92, v96, v173
	v_pk_add_f32 v[90:91], v[154:155], v[90:91]
	v_exp_f32_e32 v109, v92
	v_add_f32_e32 v92, v97, v172
	v_pk_add_f32 v[90:91], v[156:157], v[90:91]
	v_exp_f32_e32 v177, v92
	v_pk_add_f32 v[90:91], v[158:159], v[90:91]
	s_nop 0
	v_pk_add_f32 v[90:91], v[106:107], v[90:91]
	s_nop 0
	v_pk_add_f32 v[90:91], v[174:175], v[90:91]
	s_nop 0
	v_pk_add_f32 v[90:91], v[108:109], v[90:91]
	s_nop 0
	v_pk_add_f32 v[90:91], v[176:177], v[90:91]
	s_nop 0
	v_pk_add_f32 v[128:129], v[128:129], v[90:91]
	s_setprio 1
	v_cvt_pk_bf16_f32 v90, v130, v132
	v_cvt_pk_bf16_f32 v91, v134, v136
	v_cvt_pk_bf16_f32 v92, v138, v140
	v_cvt_pk_bf16_f32 v93, v148, v150
	v_cvt_pk_bf16_f32 v94, v131, v133
	v_cvt_pk_bf16_f32 v95, v135, v137
	v_cvt_pk_bf16_f32 v96, v139, v141
	v_cvt_pk_bf16_f32 v97, v149, v151
	s_nop 0
	v_mfma_f32_16x16x32_bf16 v[50:53], v[58:61], v[90:93], v[50:53]
	v_mfma_f32_16x16x32_bf16 v[14:17], v[58:61], v[94:97], v[14:17]
	v_cvt_pk_bf16_f32 v58, v152, v154
	v_cvt_pk_bf16_f32 v59, v156, v158
	v_cvt_pk_bf16_f32 v60, v106, v174
	v_mfma_f32_16x16x32_bf16 v[46:49], v[66:69], v[90:93], v[46:49]
	v_cvt_pk_bf16_f32 v61, v108, v176
	v_mfma_f32_16x16x32_bf16 v[10:13], v[66:69], v[94:97], v[10:13]
	v_cvt_pk_bf16_f32 v66, v153, v155
	v_cvt_pk_bf16_f32 v67, v157, v159
	v_cvt_pk_bf16_f32 v68, v107, v175
	v_mfma_f32_16x16x32_bf16 v[22:25], v[74:77], v[90:93], v[22:25]
	v_cvt_pk_bf16_f32 v69, v109, v177
	v_mfma_f32_16x16x32_bf16 v[6:9], v[74:77], v[94:97], v[6:9]
	v_mfma_f32_16x16x32_bf16 v[18:21], v[82:85], v[90:93], v[18:21]
	v_mfma_f32_16x16x32_bf16 v[2:5], v[82:85], v[94:97], v[2:5]
	v_mfma_f32_16x16x32_bf16 v[50:53], v[62:65], v[58:61], v[50:53]
	v_mfma_f32_16x16x32_bf16 v[14:17], v[62:65], v[66:69], v[14:17]
	v_mfma_f32_16x16x32_bf16 v[46:49], v[70:73], v[58:61], v[46:49]
	v_mfma_f32_16x16x32_bf16 v[10:13], v[70:73], v[66:69], v[10:13]
	v_mfma_f32_16x16x32_bf16 v[22:25], v[78:81], v[58:61], v[22:25]
	v_mfma_f32_16x16x32_bf16 v[6:9], v[78:81], v[66:69], v[6:9]
	v_mfma_f32_16x16x32_bf16 v[18:21], v[86:89], v[58:61], v[18:21]
	v_mfma_f32_16x16x32_bf16 v[2:5], v[86:89], v[66:69], v[2:5]
	s_setprio 0
	v_mov_b32_e32 v59, v128
	v_mov_b32_e32 v58, v129
	s_branch .LBB0_368

; #define ATT_LOAD(kt) do { const long kb_ = (long)(kt) * 64; \
;         rk0 = *(const u32x4*)(a.k + (kb_ + kkey0) * a.k_rs + kpart0 * 8); \
;         if (DQK == 96 && tid < 256) rk1 = *(const u32x4*)(a.k + (kb_ + kkey1) * a.k_rs + kpart1 * 8); \
;         rv0 = *(const u32x2*)(a.v + (kb_ + 2 * vkp) * a.v_rs + vdg * 4); rv1 = *(const u32x2*)(a.v + (kb_ + 2 * vkp + 1) * a.v_rs + vdg * 4); } while (0)
; template <int DQK, int MODE>
; __device__ __forceinline__ void attn_unit(LAS unsigned char* lds, const AttnArgs& a, const unsigned char* lut) {
;     ...
;     const int kkey0 = tid / KCH, kpart0 = tid % KCH; const int kkey1 = (tid + 512) / KCH, kpart1 = (tid + 512) % KCH;
;     const int vkp = tid & 31, vdg = tid >> 5;
;     ...
;     ATT_LOAD(kt_lo);
;     ATT_STORE(0);
;     if (kt_lo < kt_hi) ATT_LOAD(kt_lo + 1);
.LBB0_408:
	s_or_b64 exec, exec, s[38:39]
	s_ashr_i32 s31, s30, 31
	s_lshl_b64 s[38:39], s[30:31], 24
	v_readlane_b32 s20, v252, 61
	v_readlane_b32 s21, v252, 62
	s_add_u32 s22, s20, s38
	s_addc_u32 s23, s21, s39
	s_lshl_b32 s20, s13, 7
	s_ashr_i32 s21, s20, 31
	s_lshl_b64 s[40:41], s[20:21], 1
	v_lshlrev_b32_e32 v0, 1, v80
	s_add_u32 s20, s22, s40
	v_and_b32_e32 v8, 62, v0
	s_addc_u32 s21, s23, s41
	v_lshlrev_b32_e32 v0, 11, v8
	v_lshl_add_u64 v[4:5], s[20:21], 0, v[0:1]
	v_ashrrev_i32_e32 v0, 3, v80
	v_and_b32_e32 v76, -4, v0
	v_ashrrev_i32_e32 v77, 31, v76
	v_lshl_add_u64 v[4:5], v[76:77], 1, v[4:5]
	global_load_dwordx2 v[132:133], v[4:5], off offset:128
	global_load_dwordx2 v[134:135], v[4:5], off offset:2176
	s_movk_i32 s20, 0x68
	v_mul_lo_u32 v9, v6, s20
	v_lshlrev_b32_e32 v131, 1, v9
	v_lshlrev_b32_e32 v146, 1, v72
	s_movk_i32 s20, 0xd0
	v_add3_u32 v9, 0, v131, v146
	v_mul_lo_u32 v147, v82, s20
	v_lshlrev_b32_e32 v148, 4, v7
	s_waitcnt vmcnt(0)
	ds_write_b128 v9, v[58:61]
	s_and_saveexec_b64 s[44:45], s[36:37]
	v_add3_u32 v7, 0, v147, v148
	ds_write_b128 v7, v[62:65]
	s_or_b64 exec, exec, s[44:45]
	s_movk_i32 s20, 0x48
	v_mul_lo_u32 v9, v76, s20
	v_lshlrev_b32_e32 v149, 1, v9
	v_and_b32_e32 v10, 32, v8
	v_lshlrev_b32_e32 v150, 1, v10
	v_and_b32_e32 v10, 12, v8
	v_lshl_or_b32 v150, v10, 2, v150
	v_and_b32_e32 v10, 16, v8
	v_lshrrev_b32_e32 v10, 1, v10
	v_or_b32_e32 v150, v150, v10
	v_and_b32_e32 v10, 2, v8
	v_lshl_or_b32 v150, v10, 1, v150
	s_waitcnt vmcnt(1)
	v_and_b32_e32 v7, 0xffff, v132
	v_add3_u32 v8, 0, v149, v150
	v_lshrrev_b32_e32 v9, 16, v132
	s_waitcnt vmcnt(0)
	v_lshl_or_b32 v7, v134, 16, v7
	v_and_or_b32 v9, v134, s69, v9
	v_add_u32_e32 v10, 0x3800, v8
	ds_write2_b32 v10, v7, v9 offset1:36
	v_and_b32_e32 v7, 0xffff, v133
	v_or_b32_e32 v0, 3, v0
	s_sub_i32 s15, 0x1fc0, s15
	v_lshl_or_b32 v7, v135, 16, v7
	v_mul_lo_u32 v0, v0, s20
	s_ashr_i32 s15, s15, 6
	ds_write_b32 v8, v7 offset:14624
	v_lshrrev_b32_e32 v7, 16, v133
	v_lshlrev_b32_e32 v151, 1, v0
	v_and_or_b32 v7, v135, s69, v7
	v_add3_u32 v0, 0, v151, v150
	s_cmp_lt_i32 s15, 1
	ds_write_b32 v0, v7 offset:14336
	s_cbranch_scc1 .LBB0_414
	v_add_co_u32_e32 v2, vcc, 0x18000, v2
	s_nop 1
	v_addc_co_u32_e32 v3, vcc, 0, v3, vcc
	global_load_dwordx4 v[58:61], v[2:3], off
	s_and_saveexec_b64 s[44:45], s[36:37]
	s_cbranch_execz .LBB0_413
	v_add_u32_e32 v0, 64, v82
	v_mov_b64_e32 v[2:3], s[42:43]
	v_mad_i64_i32 v[2:3], s[20:21], v0, s46, v[2:3]
	v_lshl_add_u64 v[2:3], v[74:75], 1, v[2:3]
	global_load_dwordx4 v[62:65], v[2:3], off

; #define ATT_LOAD(kt) do { const long kb_ = (long)(kt) * 64; \
;         rk0 = *(const u32x4*)(a.k + (kb_ + kkey0) * a.k_rs + kpart0 * 8); \
;         if (DQK == 96 && tid < 256) rk1 = *(const u32x4*)(a.k + (kb_ + kkey1) * a.k_rs + kpart1 * 8); \
;         rv0 = *(const u32x2*)(a.v + (kb_ + 2 * vkp) * a.v_rs + vdg * 4); rv1 = *(const u32x2*)(a.v + (kb_ + 2 * vkp + 1) * a.v_rs + vdg * 4); } while (0)
; template <int DQK, int MODE>
; __device__ __forceinline__ void attn_unit(LAS unsigned char* lds, const AttnArgs& a, const unsigned char* lut) {
;     ...
;     bf16x8 qf[2][DQK / 32];
; #pragma unroll
;     for (int qt = 0; qt < 2; ++qt)
; #pragma unroll
;         for (int ks = 0; ks < DQK / 32; ++ks) qf[qt][ks] = *(const bf16x8*)(a.q + (long)(qi + qt * 16) * a.q_rs + ks * 32 + lg * 8);
;     float lsum[2]; lsum[0] = (lg == 0) ? a.l_init : 0.f; lsum[1] = lsum[0];
;     const float nb = -a.bound;
;     f32x4 o[2][4];
; #pragma unroll
;     for (int qt = 0; qt < 2; ++qt)
; #pragma unroll
;         for (int d = 0; d < 4; ++d) o[qt][d] = (f32x4){0.f, 0.f, 0.f, 0.f};
;     u32x4 rk0, rk1; u32x2 rv0, rv1;
;     const int kkey0 = tid / KCH, kpart0 = tid % KCH; const int kkey1 = (tid + 512) / KCH, kpart1 = (tid + 512) % KCH;
;     const int vkp = tid & 31, vdg = tid >> 5;
;     ...
;     ATT_LOAD(kt_lo);
;     ATT_STORE(0);
;     if (kt_lo < kt_hi) ATT_LOAD(kt_lo + 1);
;     unsigned long long mwn0 = 0ull, mwn1 = 0ull;
;     if (MODE == 2) { mwn0 = a.mask[(long)qi * 128 + kt_lo]; mwn1 = a.mask[(long)(qi + 16) * 128 + kt_lo]; }
;     __syncthreads();
;     for (int kt = kt_lo; kt <= kt_hi; ++kt) {
.LBB0_414:
	v_lshlrev_b32_e32 v153, 4, v81
	v_ashrrev_i32_e32 v129, 31, v128
	v_ashrrev_i32_e32 v127, 31, v126
	v_mad_i64_i32 v[78:79], s[20:21], v6, s46, 0
	s_mov_b64 s[42:43], -1
	s_cmp_gt_i32 s15, -1
	v_lshlrev_b32_e32 v152, 2, v81
	s_waitcnt lgkmcnt(0)
	s_barrier
	s_cbranch_scc0 .LBB0_600
	s_addk_i32 s16, 0x1f1f
	s_mul_i32 s21, s30, 0xc00000
	v_readlane_b32 s22, v254, 6
	s_mul_hi_i32 s20, s30, 0xc00000
	s_add_u32 s21, s22, s21
	v_readlane_b32 s22, v254, 7
	s_addc_u32 s20, s22, s20
	s_add_u32 s0, s0, s21
	s_addc_u32 s1, s1, s20
	v_mov_b64_e32 v[2:3], s[0:1]
	v_mad_i64_i32 v[2:3], s[20:21], v82, s46, v[2:3]
	v_readlane_b32 s20, v254, 23
	s_add_u32 s20, s20, s38
	v_readlane_b32 s21, v254, 24
	s_addc_u32 s21, s21, s39
	v_lshl_add_u64 v[136:137], v[74:75], 1, v[2:3]
	v_and_b32_e32 v2, 31, v80
	s_add_u32 s20, s40, s20
	v_lshlrev_b32_e32 v2, 12, v2
	v_mov_b32_e32 v3, v1
	s_addc_u32 s21, s41, s21
	v_lshl_add_u64 v[2:3], s[20:21], 0, v[2:3]
	v_lshl_add_u64 v[138:139], v[76:77], 1, v[2:3]
	v_lshl_add_u64 v[2:3], s[0:1], 0, v[78:79]
	s_lshl_b32 s0, s17, 8
	s_add_i32 s0, s0, s19
	s_addk_i32 s0, 0x1f00
	v_lshlrev_b32_e32 v0, 2, v81
	v_lshl_add_u64 v[140:141], v[72:73], 1, v[2:3]
	v_add_u32_e32 v2, s0, v70
	v_sub_u32_e32 v2, v2, v0
	s_lshl_b32 s0, s18, 8
	v_mov_b32_e32 v4, v1
	v_mov_b32_e32 v5, v1
	v_xor_b32_e32 v66, 0x80000000, v66
	v_mul_u32_u24_e32 v154, 0xd0, v70
	v_mul_u32_u24_e32 v155, 0x90, v70
	v_subrev_u32_e32 v156, s0, v2
	v_mov_b32_e32 v2, v1
	v_mov_b32_e32 v3, v1
	v_mov_b32_e32 v70, 0
	v_mov_b64_e32 v[8:9], v[4:5]
	v_mov_b64_e32 v[12:13], v[4:5]
	v_mov_b64_e32 v[16:17], v[4:5]
	v_mov_b64_e32 v[20:21], v[4:5]
	v_mov_b64_e32 v[24:25], v[4:5]
	v_mov_b64_e32 v[28:29], v[4:5]
	v_mov_b64_e32 v[32:33], v[4:5]
	v_mov_b32_e32 v67, v66
	v_mov_b32_e32 v68, v66
	v_mov_b32_e32 v69, v66
	s_mov_b32 s18, 0
	v_mov_b32_e32 v142, v1
	v_mov_b32_e32 v143, v1
	s_mov_b32 s17, 63
	v_mov_b64_e32 v[6:7], v[2:3]
	v_mov_b64_e32 v[10:11], v[2:3]
	v_mov_b64_e32 v[14:15], v[2:3]
	v_mov_b64_e32 v[18:19], v[2:3]
	v_mov_b64_e32 v[22:23], v[2:3]
	v_mov_b64_e32 v[26:27], v[2:3]
	v_mov_b64_e32 v[30:31], v[2:3]
	v_mov_b32_e32 v71, v70
	s_and_b32 s20, s18, 1
	s_cmp_ge_i32 s18, s15
	s_cbranch_scc0 .LBB0_418

; template <int DQK, int VAR> ...
;     ...
;         __builtin_amdgcn_sched_barrier(0);
;         __builtin_amdgcn_s_setprio(1);
; #pragma unroll
;         for (int c = 0; c < 2; ++c) {
;             s[0][ch * 2 + c] = (f32x4){sinit, sinit, sinit, sinit}; s[1][ch * 2 + c] = s[0][ch * 2 + c];
; #pragma unroll
;             for (int ks = 0; ks < DQK / 32; ++ks) {
;                 s[0][ch * 2 + c] = __builtin_amdgcn_mfma_f32_16x16x32_bf16(kfr[c][ks], qf[0][ks], s[0][ch * 2 + c], 0, 0, 0);
;                 s[1][ch * 2 + c] = __builtin_amdgcn_mfma_f32_16x16x32_bf16(kfr[c][ks], qf[1][ks], s[1][ch * 2 + c], 0, 0, 0);
;             }
;         }
;         __builtin_amdgcn_s_setprio(0);
;         __builtin_amdgcn_sched_barrier(0);
;     }
;     __builtin_amdgcn_s_setprio(0);
;     __builtin_amdgcn_sched_barrier(0);
; #pragma unroll
;     for (int kk = 0; kk < 2; ++kk)
; #pragma unroll
;         for (int dt = 0; dt < 4; ++dt) {
;             const LAS bf16_t* vp = sVt + (dt * 16 + lr) * VP + kk * 32 + lg * 4;
;             const u32x2 v0 = *(const LAS u32x2*)vp, v1 = *(const LAS u32x2*)(vp + 16);
;             vfr[kk][dt].x = v0.x; vfr[kk][dt].y = v0.y; vfr[kk][dt].z = v1.x; vfr[kk][dt].w = v1.y;
;         }
;     __builtin_amdgcn_sched_barrier(0);
; #pragma unroll
;     for (int qt = 0; qt < 2; ++qt) {
;         const int dq = qi + qt * 16 - key0 - lg * 4;
;         const LAS float* bp = sBias + (dq + 33);
;         float ps = 0.f;
; #pragma unroll
;         for (int c = 0; c < 4; ++c)
; #pragma unroll
;             for (int j = 0; j < 4; ++j) {
;                 float val = s[qt][c][j]; float pv;
;                 if (VAR == 0) pv = fexp2(val);
;                 else if (VAR == 1) { pv = fexp2(val); pv = (dq >= c * 16 + j) ? pv : 0.f; }
;                 else if (VAR == 2) { pv = fexp2(val + bp[63 - (c * 16 + j)]); }
;                 else if (VAR == 3) { pv = fexp2(val); pv = __uint_as_float(__float_as_uint(pv) & (unsigned)__builtin_amdgcn_sbfe((int)(c < 2 ? mlo[qt] : mhi[qt]), (c & 1) * 16 + j, 1)); }
;                 else { pv = fexp2(val + bp[63 - (c * 16 + j)]); pv = __uint_as_float(__float_as_uint(pv) & (unsigned)__builtin_amdgcn_sbfe((int)(c < 2 ? mlo[qt] : mhi[qt]), (c & 1) * 16 + j, 1)); }
;                 s[qt][c][j] = pv; ps += pv;
;             }
;         lsum[qt] += ps;
;     }
;     __builtin_amdgcn_s_setprio(1);
; #pragma unroll
.LBB0_424:
	s_mulk_i32 s20, 0x6000
	s_add_i32 s20, s20, 0
	v_add_u32_e32 v70, s20, v130
	v_add_u32_e32 v161, v70, v154
	ds_read_b128 v[90:93], v161
	ds_read_b128 v[86:89], v161 offset:64
	ds_read_b128 v[82:85], v161 offset:128
	ds_read_b128 v[78:81], v161 offset:3328
	ds_read_b128 v[74:77], v161 offset:3392
	ds_read_b128 v[70:73], v161 offset:3456
	v_add3_u32 v94, s20, v153, v155
	s_cmp_gt_i32 s17, s14
	s_mov_b64 s[0:1], -1
	v_add_u32_e32 v157, 0x3800, v94
	s_cbranch_scc1 .LBB0_426
	s_setprio 1
	s_waitcnt lgkmcnt(5)
	v_mfma_f32_16x16x32_bf16 v[94:97], v[90:93], v[34:37], v[66:69]
	v_mfma_f32_16x16x32_bf16 v[98:101], v[90:93], v[46:49], v[66:69]
	s_waitcnt lgkmcnt(2)
	v_mfma_f32_16x16x32_bf16 v[102:105], v[78:81], v[34:37], v[66:69]
	v_mfma_f32_16x16x32_bf16 v[106:109], v[78:81], v[46:49], v[66:69]
	v_mfma_f32_16x16x32_bf16 v[94:97], v[86:89], v[38:41], v[94:97]
	v_mfma_f32_16x16x32_bf16 v[98:101], v[86:89], v[50:53], v[98:101]
	s_waitcnt lgkmcnt(1)
	v_mfma_f32_16x16x32_bf16 v[102:105], v[74:77], v[38:41], v[102:105]
	v_mfma_f32_16x16x32_bf16 v[106:109], v[74:77], v[50:53], v[106:109]
	v_mfma_f32_16x16x32_bf16 v[94:97], v[82:85], v[42:45], v[94:97]
	v_mfma_f32_16x16x32_bf16 v[98:101], v[82:85], v[54:57], v[98:101]
	s_waitcnt lgkmcnt(0)
	v_mfma_f32_16x16x32_bf16 v[102:105], v[70:73], v[42:45], v[102:105]
	v_mfma_f32_16x16x32_bf16 v[106:109], v[70:73], v[54:57], v[106:109]
	s_setprio 0
	ds_read_b128 v[110:113], v161 offset:6656
	ds_read_b128 v[114:117], v161 offset:6720
	ds_read_b128 v[118:121], v161 offset:6784
	ds_read_b128 v[122:125], v161 offset:9984
	ds_read_b128 v[162:165], v161 offset:10048
	ds_read_b128 v[166:169], v161 offset:10112
	s_setprio 1
	s_waitcnt lgkmcnt(5)
	v_mfma_f32_16x16x32_bf16 v[170:173], v[110:113], v[34:37], v[66:69]
	v_mfma_f32_16x16x32_bf16 v[110:113], v[110:113], v[46:49], v[66:69]
	s_waitcnt lgkmcnt(4)
	v_mfma_f32_16x16x32_bf16 v[170:173], v[114:117], v[38:41], v[170:173]
	v_mfma_f32_16x16x32_bf16 v[110:113], v[114:117], v[50:53], v[110:113]
	s_waitcnt lgkmcnt(3)
	v_mfma_f32_16x16x32_bf16 v[114:117], v[118:121], v[42:45], v[170:173]
	v_mfma_f32_16x16x32_bf16 v[110:113], v[118:121], v[54:57], v[110:113]
	s_waitcnt lgkmcnt(2)
	v_mfma_f32_16x16x32_bf16 v[118:121], v[122:125], v[34:37], v[66:69]
	v_mfma_f32_16x16x32_bf16 v[122:125], v[122:125], v[46:49], v[66:69]
	s_waitcnt lgkmcnt(1)
	v_mfma_f32_16x16x32_bf16 v[118:121], v[162:165], v[38:41], v[118:121]
	v_mfma_f32_16x16x32_bf16 v[122:125], v[162:165], v[50:53], v[122:125]
	s_waitcnt lgkmcnt(0)
	v_mfma_f32_16x16x32_bf16 v[118:121], v[166:169], v[42:45], v[118:121]
	v_mfma_f32_16x16x32_bf16 v[122:125], v[166:169], v[54:57], v[122:125]
	s_setprio 0
	s_setprio 0
	ds_read_b128 v[162:165], v157
	ds_read_b128 v[166:169], v157 offset:2304
	ds_read_b128 v[170:173], v157 offset:4608
	ds_read_b128 v[174:177], v157 offset:6912
	ds_read_b128 v[178:181], v157 offset:64
	ds_read_b128 v[182:185], v157 offset:2368
	ds_read_b128 v[186:189], v157 offset:4672
	ds_read_b128 v[218:221], v157 offset:6976
	v_exp_f32_e32 v191, v94
	v_exp_f32_e32 v190, v98
	v_exp_f32_e32 v201, v95
	v_exp_f32_e32 v200, v99
	v_exp_f32_e32 v215, v96
	v_exp_f32_e32 v214, v100
	v_exp_f32_e32 v223, v97
	v_exp_f32_e32 v222, v101
	v_exp_f32_e32 v225, v102
	v_exp_f32_e32 v224, v106
	v_pk_add_f32 v[94:95], v[190:191], 0 op_sel_hi:[1,0]
	v_exp_f32_e32 v231, v103
	v_exp_f32_e32 v230, v107
	v_pk_add_f32 v[94:95], v[200:201], v[94:95]
	v_exp_f32_e32 v233, v104
	v_exp_f32_e32 v232, v108
	v_pk_add_f32 v[94:95], v[214:215], v[94:95]
	v_exp_f32_e32 v235, v105
	v_exp_f32_e32 v234, v109
	v_pk_add_f32 v[94:95], v[222:223], v[94:95]
	v_exp_f32_e32 v237, v114
	v_exp_f32_e32 v236, v110
	v_pk_add_f32 v[94:95], v[94:95], v[224:225]
	v_exp_f32_e32 v239, v115
	v_pk_add_f32 v[94:95], v[230:231], v[94:95]
	v_exp_f32_e32 v238, v111
	v_exp_f32_e32 v241, v116
	v_pk_add_f32 v[94:95], v[232:233], v[94:95]
	v_exp_f32_e32 v240, v112
	v_exp_f32_e32 v243, v117
	v_pk_add_f32 v[94:95], v[234:235], v[94:95]
	v_exp_f32_e32 v242, v113
	v_exp_f32_e32 v245, v118
	v_pk_add_f32 v[94:95], v[94:95], v[236:237]
	v_exp_f32_e32 v244, v122
	v_exp_f32_e32 v247, v119
	v_exp_f32_e32 v246, v123
	v_pk_add_f32 v[94:95], v[238:239], v[94:95]
	v_exp_f32_e32 v249, v120
	v_exp_f32_e32 v248, v124
	v_pk_add_f32 v[94:95], v[240:241], v[94:95]
	v_exp_f32_e32 v203, v121
	v_pk_add_f32 v[94:95], v[242:243], v[94:95]
	v_exp_f32_e32 v202, v125
	v_pk_add_f32 v[94:95], v[94:95], v[244:245]
	s_nop 0
	v_pk_add_f32 v[94:95], v[246:247], v[94:95]
	s_nop 0
	v_pk_add_f32 v[94:95], v[248:249], v[94:95]
	s_nop 0
	v_pk_add_f32 v[144:145], v[202:203], v[94:95]
	s_setprio 1
	v_cvt_pk_bf16_f32 v94, v191, v201
	v_cvt_pk_bf16_f32 v95, v215, v223
	v_cvt_pk_bf16_f32 v96, v225, v231
	v_cvt_pk_bf16_f32 v97, v233, v235
	v_cvt_pk_bf16_f32 v98, v190, v200
	v_cvt_pk_bf16_f32 v99, v214, v222
	v_cvt_pk_bf16_f32 v100, v224, v230
	v_cvt_pk_bf16_f32 v101, v232, v234
	s_mov_b64 s[0:1], 0
	s_waitcnt lgkmcnt(7)
	v_mfma_f32_16x16x32_bf16 v[30:33], v[162:165], v[94:97], v[30:33]
	v_mfma_f32_16x16x32_bf16 v[14:17], v[162:165], v[98:101], v[14:17]
	s_waitcnt lgkmcnt(6)
	v_mfma_f32_16x16x32_bf16 v[26:29], v[166:169], v[94:97], v[26:29]
	v_mfma_f32_16x16x32_bf16 v[10:13], v[166:169], v[98:101], v[10:13]
	s_waitcnt lgkmcnt(5)
	v_mfma_f32_16x16x32_bf16 v[22:25], v[170:173], v[94:97], v[22:25]
	v_mfma_f32_16x16x32_bf16 v[6:9], v[170:173], v[98:101], v[6:9]
	v_cvt_pk_bf16_f32 v170, v237, v239
	v_cvt_pk_bf16_f32 v171, v241, v243
	v_cvt_pk_bf16_f32 v172, v245, v247
	s_waitcnt lgkmcnt(4)
	v_mfma_f32_16x16x32_bf16 v[18:21], v[174:177], v[94:97], v[18:21]
	v_cvt_pk_bf16_f32 v173, v249, v203
	v_mfma_f32_16x16x32_bf16 v[2:5], v[174:177], v[98:101], v[2:5]
	v_cvt_pk_bf16_f32 v174, v236, v238
	v_cvt_pk_bf16_f32 v175, v240, v242
	v_cvt_pk_bf16_f32 v176, v244, v246
	s_waitcnt lgkmcnt(3)
	v_mfma_f32_16x16x32_bf16 v[30:33], v[178:181], v[170:173], v[30:33]
	v_cvt_pk_bf16_f32 v177, v248, v202
	s_nop 0
	v_mfma_f32_16x16x32_bf16 v[14:17], v[178:181], v[174:177], v[14:17]
	s_waitcnt lgkmcnt(2)
	v_mfma_f32_16x16x32_bf16 v[26:29], v[182:185], v[170:173], v[26:29]
	v_mfma_f32_16x16x32_bf16 v[10:13], v[182:185], v[174:177], v[10:13]
	s_waitcnt lgkmcnt(1)
	v_mfma_f32_16x16x32_bf16 v[22:25], v[186:189], v[170:173], v[22:25]
	v_mfma_f32_16x16x32_bf16 v[6:9], v[186:189], v[174:177], v[6:9]
	s_waitcnt lgkmcnt(0)
	v_mfma_f32_16x16x32_bf16 v[18:21], v[218:221], v[170:173], v[18:21]
	v_mfma_f32_16x16x32_bf16 v[2:5], v[218:221], v[174:177], v[2:5]
; #define LAS __attribute__((address_space(3)))
; template <int DQK, int VAR> ...
;     ...
;     for (int ch = 0; ch < 2; ++ch) {
;         bf16x8 kfr[2][DQK / 32];
; #pragma unroll
;         for (int c = 0; c < 2; ++c)
; #pragma unroll
;             for (int ks = 0; ks < DQK / 32; ++ks) kfr[c][ks] = *(const LAS bf16x8*)(sK + ((ch * 2 + c) * 16 + lr) * KP + ks * 32 + lg * 8);
;         __builtin_amdgcn_sched_barrier(0);
;         __builtin_amdgcn_s_setprio(1);
; #pragma unroll
;         for (int c = 0; c < 2; ++c) {
;             s[0][ch * 2 + c] = (f32x4){sinit, sinit, sinit, sinit}; s[1][ch * 2 + c] = s[0][ch * 2 + c];
; #pragma unroll
;             for (int ks = 0; ks < DQK / 32; ++ks) {
;                 s[0][ch * 2 + c] = __builtin_amdgcn_mfma_f32_16x16x32_bf16(kfr[c][ks], qf[0][ks], s[0][ch * 2 + c], 0, 0, 0);
;                 s[1][ch * 2 + c] = __builtin_amdgcn_mfma_f32_16x16x32_bf16(kfr[c][ks], qf[1][ks], s[1][ch * 2 + c], 0, 0, 0);
;             }
;         }
;         __builtin_amdgcn_s_setprio(0);
;         __builtin_amdgcn_sched_barrier(0);
;     }
.LBB0_426:
	s_andn2_b64 vcc, exec, s[0:1]
	s_cbranch_vccnz .LBB0_428
	s_setprio 1
	s_waitcnt lgkmcnt(5)
	v_mfma_f32_16x16x32_bf16 v[94:97], v[90:93], v[34:37], v[66:69]
	v_mfma_f32_16x16x32_bf16 v[90:93], v[90:93], v[46:49], v[66:69]
	s_waitcnt lgkmcnt(4)
	v_mfma_f32_16x16x32_bf16 v[94:97], v[86:89], v[38:41], v[94:97]
	v_mfma_f32_16x16x32_bf16 v[86:89], v[86:89], v[50:53], v[90:93]
	s_waitcnt lgkmcnt(3)
	v_mfma_f32_16x16x32_bf16 v[90:93], v[82:85], v[42:45], v[94:97]
	v_mfma_f32_16x16x32_bf16 v[82:85], v[82:85], v[54:57], v[86:89]
	s_waitcnt lgkmcnt(2)
	v_mfma_f32_16x16x32_bf16 v[86:89], v[78:81], v[34:37], v[66:69]
	v_mfma_f32_16x16x32_bf16 v[78:81], v[78:81], v[46:49], v[66:69]
	s_waitcnt lgkmcnt(1)
	v_mfma_f32_16x16x32_bf16 v[86:89], v[74:77], v[38:41], v[86:89]
	v_mfma_f32_16x16x32_bf16 v[74:77], v[74:77], v[50:53], v[78:81]
	s_waitcnt lgkmcnt(0)
	v_mfma_f32_16x16x32_bf16 v[78:81], v[70:73], v[42:45], v[86:89]
	v_mfma_f32_16x16x32_bf16 v[70:73], v[70:73], v[54:57], v[74:77]
	s_setprio 0
	s_nop 3
	ds_read_b128 v[74:77], v161 offset:6656
	ds_read_b128 v[86:89], v161 offset:6720
	ds_read_b128 v[94:97], v161 offset:6784
	ds_read_b128 v[98:101], v161 offset:9984
	ds_read_b128 v[102:105], v161 offset:10048
	ds_read_b128 v[106:109], v161 offset:10112
	s_setprio 1
	s_waitcnt lgkmcnt(5)
	v_mfma_f32_16x16x32_bf16 v[110:113], v[74:77], v[34:37], v[66:69]
	v_mfma_f32_16x16x32_bf16 v[74:77], v[74:77], v[46:49], v[66:69]
	s_waitcnt lgkmcnt(4)
	v_mfma_f32_16x16x32_bf16 v[110:113], v[86:89], v[38:41], v[110:113]
	v_mfma_f32_16x16x32_bf16 v[74:77], v[86:89], v[50:53], v[74:77]
	s_waitcnt lgkmcnt(3)
	v_mfma_f32_16x16x32_bf16 v[86:89], v[94:97], v[42:45], v[110:113]
	v_mfma_f32_16x16x32_bf16 v[74:77], v[94:97], v[54:57], v[74:77]
	s_waitcnt lgkmcnt(2)
	v_mfma_f32_16x16x32_bf16 v[94:97], v[98:101], v[34:37], v[66:69]
	v_mfma_f32_16x16x32_bf16 v[98:101], v[98:101], v[46:49], v[66:69]
	s_waitcnt lgkmcnt(1)
	v_mfma_f32_16x16x32_bf16 v[94:97], v[102:105], v[38:41], v[94:97]
	v_mfma_f32_16x16x32_bf16 v[98:101], v[102:105], v[50:53], v[98:101]
	s_waitcnt lgkmcnt(0)
; template <int DQK, int VAR> ...
;     ...
; #pragma unroll
;     for (int kk = 0; kk < 2; ++kk)
; #pragma unroll
;         for (int dt = 0; dt < 4; ++dt) {
;             const LAS bf16_t* vp = sVt + (dt * 16 + lr) * VP + kk * 32 + lg * 4;
;             const u32x2 v0 = *(const LAS u32x2*)vp, v1 = *(const LAS u32x2*)(vp + 16);
;             vfr[kk][dt].x = v0.x; vfr[kk][dt].y = v0.y; vfr[kk][dt].z = v1.x; vfr[kk][dt].w = v1.y;
;         }
;     __builtin_amdgcn_sched_barrier(0);
; #pragma unroll
;     for (int qt = 0; qt < 2; ++qt) {
;         const int dq = qi + qt * 16 - key0 - lg * 4;
;         const LAS float* bp = sBias + (dq + 33);
;         float ps = 0.f;
; #pragma unroll
;         for (int c = 0; c < 4; ++c)
; #pragma unroll
;             for (int j = 0; j < 4; ++j) {
;                 float val = s[qt][c][j]; float pv;
;                 if (VAR == 0) pv = fexp2(val);
;                 else if (VAR == 1) { pv = fexp2(val); pv = (dq >= c * 16 + j) ? pv : 0.f; }
;                 else if (VAR == 2) { pv = fexp2(val + bp[63 - (c * 16 + j)]); }
;                 else if (VAR == 3) { pv = fexp2(val); pv = __uint_as_float(__float_as_uint(pv) & (unsigned)__builtin_amdgcn_sbfe((int)(c < 2 ? mlo[qt] : mhi[qt]), (c & 1) * 16 + j, 1)); }
;                 else { pv = fexp2(val + bp[63 - (c * 16 + j)]); pv = __uint_as_float(__float_as_uint(pv) & (unsigned)__builtin_amdgcn_sbfe((int)(c < 2 ? mlo[qt] : mhi[qt]), (c & 1) * 16 + j, 1)); }
;                 s[qt][c][j] = pv; ps += pv;
;             }
;         lsum[qt] += ps;
;     }
;     __builtin_amdgcn_s_setprio(1);
; #pragma unroll
;     for (int kk = 0; kk < 2; ++kk) {
;         bf16x8 pb[2];
; #pragma unroll
;         for (int qt = 0; qt < 2; ++qt) {
;             u32x4 pw; pw.x = pk2(s[qt][2 * kk][0], s[qt][2 * kk][1]); pw.y = pk2(s[qt][2 * kk][2], s[qt][2 * kk][3]); pw.z = pk2(s[qt][2 * kk + 1][0], s[qt][2 * kk + 1][1]); pw.w = pk2(s[qt][2 * kk + 1][2], s[qt][2 * kk + 1][3]);
;             pb[qt] = __builtin_bit_cast(bf16x8, pw);
;         }
; #pragma unroll
;         for (int dt = 0; dt < 4; ++dt) {
;             const bf16x8 vf = __builtin_bit_cast(bf16x8, vfr[kk][dt]);
;             o[0][dt] = __builtin_amdgcn_mfma_f32_16x16x32_bf16(vf, pb[0], o[0][dt], 0, 0, 0);
;             o[1][dt] = __builtin_amdgcn_mfma_f32_16x16x32_bf16(vf, pb[1], o[1][dt], 0, 0, 0);
;         }
;     }
	v_mfma_f32_16x16x32_bf16 v[94:97], v[106:109], v[42:45], v[94:97]
	v_mfma_f32_16x16x32_bf16 v[98:101], v[106:109], v[54:57], v[98:101]
	s_setprio 0
	s_setprio 0
	ds_read_b128 v[102:105], v157
	ds_read_b128 v[106:109], v157 offset:2304
	ds_read_b128 v[110:113], v157 offset:4608
	ds_read_b128 v[114:117], v157 offset:6912
	ds_read_b128 v[118:121], v157 offset:64
	ds_read_b128 v[122:125], v157 offset:2368
	ds_read_b128 v[158:161], v157 offset:4672
	ds_read_b128 v[162:165], v157 offset:6976
	v_exp_f32_e32 v144, v79
	v_exp_f32_e32 v79, v87
	v_exp_f32_e32 v90, v90
	v_exp_f32_e32 v145, v80
	v_exp_f32_e32 v80, v82
	v_exp_f32_e32 v91, v91
	v_cmp_lt_i32_e32 vcc, 32, v156
	v_exp_f32_e32 v157, v81
	v_exp_f32_e32 v81, v83
	v_cndmask_b32_e32 v79, 0, v79, vcc
	v_add_u32_e32 v177, 16, v156
	v_cmp_lt_i32_e32 vcc, -1, v156
	v_exp_f32_e32 v92, v92
	v_exp_f32_e32 v170, v75
	v_cndmask_b32_e32 v75, 0, v90, vcc
	v_cmp_lt_i32_e32 vcc, -1, v177
	v_exp_f32_e32 v82, v84
	v_exp_f32_e32 v169, v74
	v_cndmask_b32_e32 v74, 0, v80, vcc
	v_cmp_lt_i32_e32 vcc, 0, v156
	v_exp_f32_e32 v93, v93
	v_exp_f32_e32 v172, v77
	v_cndmask_b32_e32 v77, 0, v91, vcc
	v_cmp_lt_i32_e32 vcc, 0, v177
	v_exp_f32_e32 v84, v85
	v_exp_f32_e32 v171, v76
	v_cndmask_b32_e32 v76, 0, v81, vcc
	v_cmp_lt_i32_e32 vcc, 1, v156
	v_exp_f32_e32 v78, v78
	v_exp_f32_e32 v166, v86
	v_cndmask_b32_e32 v81, 0, v92, vcc
	v_cmp_lt_i32_e32 vcc, 1, v177
	v_exp_f32_e32 v86, v70
	v_exp_f32_e32 v167, v88
	v_cndmask_b32_e32 v80, 0, v82, vcc
	v_cmp_lt_i32_e32 vcc, 2, v156
	v_exp_f32_e32 v88, v71
	s_mov_b32 s0, 0x7ffffff0
	v_cndmask_b32_e32 v83, 0, v93, vcc
	v_cmp_lt_i32_e32 vcc, 2, v177
	v_exp_f32_e32 v72, v72
	v_exp_f32_e32 v73, v73
	v_cndmask_b32_e32 v82, 0, v84, vcc
	v_cmp_lt_i32_e32 vcc, 15, v156
	v_exp_f32_e32 v168, v89
	v_pk_add_f32 v[70:71], v[74:75], 0 op_sel_hi:[1,0]
	v_cndmask_b32_e32 v85, 0, v78, vcc
	v_cmp_gt_u32_e32 vcc, s0, v156
	v_pk_add_f32 v[70:71], v[76:77], v[70:71]
	v_exp_f32_e32 v94, v94
	v_cndmask_b32_e32 v84, 0, v86, vcc
	v_cmp_lt_i32_e32 vcc, 16, v156
	v_pk_add_f32 v[70:71], v[80:81], v[70:71]
	v_exp_f32_e32 v174, v99
	v_cndmask_b32_e32 v87, 0, v144, vcc
	v_cmp_lt_i32_e32 vcc, 16, v177
	v_pk_add_f32 v[70:71], v[82:83], v[70:71]
	v_exp_f32_e32 v173, v98
	v_cndmask_b32_e32 v86, 0, v88, vcc
	v_cmp_lt_i32_e32 vcc, 17, v156
	v_pk_add_f32 v[70:71], v[70:71], v[84:85]
	v_exp_f32_e32 v95, v95
	v_cndmask_b32_e32 v89, 0, v145, vcc
	v_cmp_lt_i32_e32 vcc, 17, v177
	v_exp_f32_e32 v176, v101
	v_pk_add_f32 v[70:71], v[86:87], v[70:71]
	v_cndmask_b32_e32 v88, 0, v72, vcc
	v_cmp_lt_i32_e32 vcc, 18, v156
	v_exp_f32_e32 v175, v100
	v_pk_add_f32 v[70:71], v[88:89], v[70:71]
	v_cndmask_b32_e32 v91, 0, v157, vcc
	v_cmp_lt_i32_e32 vcc, 18, v177
	v_exp_f32_e32 v96, v96
	v_exp_f32_e32 v97, v97
	v_cndmask_b32_e32 v90, 0, v73, vcc
	v_cmp_lt_i32_e32 vcc, 31, v156
	v_pk_add_f32 v[70:71], v[90:91], v[70:71]
	s_nop 0
	v_cndmask_b32_e32 v93, 0, v166, vcc
	v_cmp_lt_i32_e32 vcc, 31, v177
	s_nop 1
	v_cndmask_b32_e32 v92, 0, v169, vcc
	v_cmp_lt_i32_e32 vcc, 32, v177
	v_pk_add_f32 v[70:71], v[70:71], v[92:93]
	s_nop 0
	v_cndmask_b32_e32 v78, 0, v170, vcc
	v_cmp_lt_i32_e32 vcc, 33, v156
	v_pk_add_f32 v[70:71], v[78:79], v[70:71]
	s_nop 0
	v_cndmask_b32_e32 v99, 0, v167, vcc
	v_cmp_lt_i32_e32 vcc, 33, v177
	s_nop 1
	v_cndmask_b32_e32 v98, 0, v171, vcc
	v_cmp_lt_i32_e32 vcc, 34, v156
	v_pk_add_f32 v[70:71], v[98:99], v[70:71]
	s_nop 0
	v_cndmask_b32_e32 v101, 0, v168, vcc
	v_cmp_lt_i32_e32 vcc, 34, v177
	s_nop 1
	v_cndmask_b32_e32 v100, 0, v172, vcc
	v_cmp_lt_i32_e32 vcc, 47, v156
	v_pk_add_f32 v[70:71], v[100:101], v[70:71]
	s_nop 0
	v_cndmask_b32_e32 v167, 0, v94, vcc
	v_cmp_lt_i32_e32 vcc, 47, v177
	s_nop 1
	v_cndmask_b32_e32 v166, 0, v173, vcc
	v_cmp_lt_i32_e32 vcc, 48, v156
	v_pk_add_f32 v[70:71], v[70:71], v[166:167]
	s_nop 0
	v_cndmask_b32_e32 v169, 0, v95, vcc
	v_cmp_lt_i32_e32 vcc, 48, v177
	s_nop 1
	v_cndmask_b32_e32 v168, 0, v174, vcc
	v_cmp_lt_i32_e32 vcc, 49, v156
	v_pk_add_f32 v[70:71], v[168:169], v[70:71]
	s_nop 0
	v_cndmask_b32_e32 v171, 0, v96, vcc
	v_cmp_lt_i32_e32 vcc, 49, v177
	s_nop 1
	v_cndmask_b32_e32 v170, 0, v175, vcc
	v_cmp_lt_i32_e32 vcc, 50, v156
	v_pk_add_f32 v[70:71], v[170:171], v[70:71]
	s_nop 0
	v_cndmask_b32_e32 v173, 0, v97, vcc
	v_cmp_lt_i32_e32 vcc, 50, v177
	s_nop 1
	v_cndmask_b32_e32 v172, 0, v176, vcc
	v_pk_add_f32 v[144:145], v[172:173], v[70:71]
	s_setprio 1
	v_cvt_pk_bf16_f32 v70, v75, v77
	v_cvt_pk_bf16_f32 v71, v81, v83
	v_cvt_pk_bf16_f32 v72, v85, v87
	v_cvt_pk_bf16_f32 v73, v89, v91
	v_cvt_pk_bf16_f32 v74, v74, v76
	v_cvt_pk_bf16_f32 v75, v80, v82
	v_cvt_pk_bf16_f32 v76, v84, v86
	v_cvt_pk_bf16_f32 v77, v88, v90
	s_waitcnt lgkmcnt(7)
	v_mfma_f32_16x16x32_bf16 v[30:33], v[102:105], v[70:73], v[30:33]
	v_mfma_f32_16x16x32_bf16 v[14:17], v[102:105], v[74:77], v[14:17]
	s_waitcnt lgkmcnt(6)
	v_mfma_f32_16x16x32_bf16 v[26:29], v[106:109], v[70:73], v[26:29]
	v_mfma_f32_16x16x32_bf16 v[10:13], v[106:109], v[74:77], v[10:13]
	s_waitcnt lgkmcnt(5)
	v_mfma_f32_16x16x32_bf16 v[22:25], v[110:113], v[70:73], v[22:25]
	v_mfma_f32_16x16x32_bf16 v[6:9], v[110:113], v[74:77], v[6:9]
	s_waitcnt lgkmcnt(4)
	v_mfma_f32_16x16x32_bf16 v[18:21], v[114:117], v[70:73], v[18:21]
	v_cvt_pk_bf16_f32 v70, v93, v79
	v_cvt_pk_bf16_f32 v71, v99, v101
	v_cvt_pk_bf16_f32 v72, v167, v169
	v_mfma_f32_16x16x32_bf16 v[2:5], v[114:117], v[74:77], v[2:5]
	v_cvt_pk_bf16_f32 v73, v171, v173
	v_cvt_pk_bf16_f32 v74, v92, v78
	v_cvt_pk_bf16_f32 v75, v98, v100
	v_cvt_pk_bf16_f32 v76, v166, v168
	v_cvt_pk_bf16_f32 v77, v170, v172
	s_waitcnt lgkmcnt(3)
	v_mfma_f32_16x16x32_bf16 v[30:33], v[118:121], v[70:73], v[30:33]
	v_mfma_f32_16x16x32_bf16 v[14:17], v[118:121], v[74:77], v[14:17]
	s_waitcnt lgkmcnt(2)
	v_mfma_f32_16x16x32_bf16 v[26:29], v[122:125], v[70:73], v[26:29]
	v_mfma_f32_16x16x32_bf16 v[10:13], v[122:125], v[74:77], v[10:13]
	s_waitcnt lgkmcnt(1)
	v_mfma_f32_16x16x32_bf16 v[22:25], v[158:161], v[70:73], v[22:25]
	v_mfma_f32_16x16x32_bf16 v[6:9], v[158:161], v[74:77], v[6:9]
	s_waitcnt lgkmcnt(0)
	v_mfma_f32_16x16x32_bf16 v[18:21], v[162:165], v[70:73], v[18:21]
	v_mfma_f32_16x16x32_bf16 v[2:5], v[162:165], v[74:77], v[2:5]
